# v80 plus: the K-loop scalar pointer updates sit only between accumulator pairs, never between the two back-to-back MFMAs of one accumulator
# baseline (speedup 1.0000x reference)
.LBB0_265:
	ds_read_b128 v[154:157], v161
	ds_read_b128 v[164:167], v161 offset:1024
	ds_read_b128 v[168:171], v161 offset:2048
	ds_read_b128 v[172:175], v161 offset:3072
	ds_read_b128 v[176:179], v162
	ds_read_b128 v[180:183], v162 offset:1024
	ds_read_b128 v[184:187], v162 offset:2048
	ds_read_b128 v[188:191], v162 offset:3072
	ds_read_b128 v[192:195], v163
	ds_read_b128 v[196:199], v163 offset:1024
	ds_read_b128 v[200:203], v163 offset:2048
	ds_read_b128 v[204:207], v163 offset:3072
	ds_read_b128 v[208:211], v163 offset:4096
	ds_read_b128 v[212:215], v163 offset:5120
	s_add_i32 m0, s33, 0xc000
	ds_read_b128 v[216:219], v163 offset:6144
	global_load_lds_dwordx4 v146, s[72:73]
	s_add_i32 m0, s33, 0xe000
	ds_read_b128 v[220:223], v163 offset:7168
	global_load_lds_dwordx4 v148, s[72:73]
	s_waitcnt vmcnt(8) lgkmcnt(0)
	s_barrier
	s_setprio 1
	v_mfma_f32_16x16x32_bf16 v[126:129], v[154:157], v[192:195], v[126:129]
	v_mfma_f32_16x16x32_bf16 v[126:129], v[164:167], v[196:199], v[126:129]
	s_add_u32 s12, s72, 0xfff00080
	v_mfma_f32_16x16x32_bf16 v[110:113], v[154:157], v[200:203], v[110:113]
	v_mfma_f32_16x16x32_bf16 v[110:113], v[164:167], v[204:207], v[110:113]
	s_addc_u32 s13, s73, -1
	v_mfma_f32_16x16x32_bf16 v[94:97], v[154:157], v[208:211], v[94:97]
	v_mfma_f32_16x16x32_bf16 v[94:97], v[164:167], v[212:215], v[94:97]
	s_cmp_eq_u32 s83, 60
	v_mfma_f32_16x16x32_bf16 v[78:81], v[154:157], v[216:219], v[78:81]
	v_mfma_f32_16x16x32_bf16 v[78:81], v[164:167], v[220:223], v[78:81]
	s_cselect_b32 s77, s55, s13
	v_mfma_f32_16x16x32_bf16 v[122:125], v[168:171], v[192:195], v[122:125]
	v_mfma_f32_16x16x32_bf16 v[122:125], v[172:175], v[196:199], v[122:125]
	s_cselect_b32 s76, s71, s12
	v_mfma_f32_16x16x32_bf16 v[106:109], v[168:171], v[200:203], v[106:109]
	v_mfma_f32_16x16x32_bf16 v[106:109], v[172:175], v[204:207], v[106:109]
	s_cselect_b32 s75, s53, s82
	v_mfma_f32_16x16x32_bf16 v[90:93], v[168:171], v[208:211], v[90:93]
	v_mfma_f32_16x16x32_bf16 v[90:93], v[172:175], v[212:215], v[90:93]
	s_cselect_b32 s74, s80, s81
	v_mfma_f32_16x16x32_bf16 v[74:77], v[168:171], v[216:219], v[74:77]
	v_mfma_f32_16x16x32_bf16 v[74:77], v[172:175], v[220:223], v[74:77]
	s_add_u32 s98, s74, 0x100000
	v_mfma_f32_16x16x32_bf16 v[118:121], v[176:179], v[192:195], v[118:121]
	v_mfma_f32_16x16x32_bf16 v[118:121], v[180:183], v[196:199], v[118:121]
	s_addc_u32 s99, s75, 0
	v_mfma_f32_16x16x32_bf16 v[102:105], v[176:179], v[200:203], v[102:105]
	v_mfma_f32_16x16x32_bf16 v[102:105], v[180:183], v[204:207], v[102:105]
	s_add_u32 s100, s76, 0x100000
	v_mfma_f32_16x16x32_bf16 v[86:89], v[176:179], v[208:211], v[86:89]
	v_mfma_f32_16x16x32_bf16 v[86:89], v[180:183], v[212:215], v[86:89]
	s_addc_u32 s101, s77, 0
	v_mfma_f32_16x16x32_bf16 v[70:73], v[176:179], v[216:219], v[70:73]
	v_mfma_f32_16x16x32_bf16 v[70:73], v[180:183], v[220:223], v[70:73]
	v_mfma_f32_16x16x32_bf16 v[114:117], v[184:187], v[192:195], v[114:117]
	v_mfma_f32_16x16x32_bf16 v[114:117], v[188:191], v[196:199], v[114:117]
	v_mfma_f32_16x16x32_bf16 v[98:101], v[184:187], v[200:203], v[98:101]
	v_mfma_f32_16x16x32_bf16 v[98:101], v[188:191], v[204:207], v[98:101]
	v_mfma_f32_16x16x32_bf16 v[82:85], v[184:187], v[208:211], v[82:85]
	v_mfma_f32_16x16x32_bf16 v[82:85], v[188:191], v[212:215], v[82:85]
	v_mfma_f32_16x16x32_bf16 v[66:69], v[184:187], v[216:219], v[66:69]
	v_mfma_f32_16x16x32_bf16 v[66:69], v[188:191], v[220:223], v[66:69]
	s_setprio 0
	s_barrier
	ds_read_b128 v[192:195], v163 offset:16384
	ds_read_b128 v[196:199], v163 offset:17408
	s_add_i32 m0, s33, 0x10000
	ds_read_b128 v[200:203], v163 offset:18432
	global_load_lds_dwordx4 v134, s[74:75]
	s_add_i32 m0, s33, 0x12000
	ds_read_b128 v[204:207], v163 offset:19456
	global_load_lds_dwordx4 v130, s[74:75]
	s_add_i32 m0, s33, 0x14000
	ds_read_b128 v[208:211], v163 offset:20480
	global_load_lds_dwordx4 v134, s[98:99]
	s_add_i32 m0, s33, 0x16000
	ds_read_b128 v[212:215], v163 offset:21504
	global_load_lds_dwordx4 v130, s[98:99]
	s_mov_b32 m0, s33
	ds_read_b128 v[216:219], v163 offset:22528
	global_load_lds_dwordx4 v136, s[76:77]
	s_add_i32 m0, s33, 0x2000
	ds_read_b128 v[220:223], v163 offset:23552
	global_load_lds_dwordx4 v132, s[76:77]
	s_waitcnt vmcnt(8) lgkmcnt(0)
	s_barrier
	s_setprio 1
	v_mfma_f32_16x16x32_bf16 v[62:65], v[154:157], v[192:195], v[62:65]
	v_mfma_f32_16x16x32_bf16 v[62:65], v[164:167], v[196:199], v[62:65]
	v_mfma_f32_16x16x32_bf16 v[46:49], v[154:157], v[200:203], v[46:49]
	v_mfma_f32_16x16x32_bf16 v[46:49], v[164:167], v[204:207], v[46:49]
	v_mfma_f32_16x16x32_bf16 v[30:33], v[154:157], v[208:211], v[30:33]
	v_mfma_f32_16x16x32_bf16 v[30:33], v[164:167], v[212:215], v[30:33]
	v_mfma_f32_16x16x32_bf16 v[14:17], v[154:157], v[216:219], v[14:17]
	v_mfma_f32_16x16x32_bf16 v[14:17], v[164:167], v[220:223], v[14:17]
	v_mfma_f32_16x16x32_bf16 v[58:61], v[168:171], v[192:195], v[58:61]
	v_mfma_f32_16x16x32_bf16 v[58:61], v[172:175], v[196:199], v[58:61]
	v_mfma_f32_16x16x32_bf16 v[42:45], v[168:171], v[200:203], v[42:45]
	v_mfma_f32_16x16x32_bf16 v[42:45], v[172:175], v[204:207], v[42:45]
	v_mfma_f32_16x16x32_bf16 v[26:29], v[168:171], v[208:211], v[26:29]
	v_mfma_f32_16x16x32_bf16 v[26:29], v[172:175], v[212:215], v[26:29]
	v_mfma_f32_16x16x32_bf16 v[10:13], v[168:171], v[216:219], v[10:13]
	v_mfma_f32_16x16x32_bf16 v[10:13], v[172:175], v[220:223], v[10:13]
	v_mfma_f32_16x16x32_bf16 v[54:57], v[176:179], v[192:195], v[54:57]
	v_mfma_f32_16x16x32_bf16 v[54:57], v[180:183], v[196:199], v[54:57]
	v_mfma_f32_16x16x32_bf16 v[38:41], v[176:179], v[200:203], v[38:41]
	v_mfma_f32_16x16x32_bf16 v[38:41], v[180:183], v[204:207], v[38:41]
	v_mfma_f32_16x16x32_bf16 v[22:25], v[176:179], v[208:211], v[22:25]
	v_mfma_f32_16x16x32_bf16 v[22:25], v[180:183], v[212:215], v[22:25]
	v_mfma_f32_16x16x32_bf16 v[6:9], v[176:179], v[216:219], v[6:9]
	v_mfma_f32_16x16x32_bf16 v[6:9], v[180:183], v[220:223], v[6:9]
	v_mfma_f32_16x16x32_bf16 v[50:53], v[184:187], v[192:195], v[50:53]
	v_mfma_f32_16x16x32_bf16 v[50:53], v[188:191], v[196:199], v[50:53]
	v_mfma_f32_16x16x32_bf16 v[34:37], v[184:187], v[200:203], v[34:37]
	v_mfma_f32_16x16x32_bf16 v[34:37], v[188:191], v[204:207], v[34:37]
	v_mfma_f32_16x16x32_bf16 v[18:21], v[184:187], v[208:211], v[18:21]
	v_mfma_f32_16x16x32_bf16 v[18:21], v[188:191], v[212:215], v[18:21]
	v_mfma_f32_16x16x32_bf16 v[2:5], v[184:187], v[216:219], v[2:5]
	v_mfma_f32_16x16x32_bf16 v[2:5], v[188:191], v[220:223], v[2:5]
	s_setprio 0
	s_barrier
	ds_read_b128 v[154:157], v226
	ds_read_b128 v[164:167], v226 offset:1024
	ds_read_b128 v[168:171], v226 offset:2048
	ds_read_b128 v[172:175], v226 offset:3072
	ds_read_b128 v[176:179], v227
	ds_read_b128 v[180:183], v227 offset:1024
	ds_read_b128 v[184:187], v227 offset:2048
	ds_read_b128 v[188:191], v227 offset:3072
	ds_read_b128 v[192:195], v163 offset:32768
	ds_read_b128 v[196:199], v163 offset:33792
	ds_read_b128 v[200:203], v163 offset:34816
	ds_read_b128 v[204:207], v163 offset:35840
	ds_read_b128 v[208:211], v163 offset:36864
	ds_read_b128 v[212:215], v163 offset:37888
	s_add_i32 m0, s33, 0x4000
	ds_read_b128 v[216:219], v163 offset:38912
	global_load_lds_dwordx4 v136, s[100:101]
	s_add_i32 m0, s33, 0x6000
	ds_read_b128 v[220:223], v163 offset:39936
	global_load_lds_dwordx4 v132, s[100:101]
	s_waitcnt vmcnt(8) lgkmcnt(0)
	s_barrier
	s_setprio 1
	v_mfma_f32_16x16x32_bf16 v[126:129], v[154:157], v[192:195], v[126:129]
	v_mfma_f32_16x16x32_bf16 v[126:129], v[164:167], v[196:199], v[126:129]
	v_mfma_f32_16x16x32_bf16 v[110:113], v[154:157], v[200:203], v[110:113]
	v_mfma_f32_16x16x32_bf16 v[110:113], v[164:167], v[204:207], v[110:113]
	v_mfma_f32_16x16x32_bf16 v[94:97], v[154:157], v[208:211], v[94:97]
	v_mfma_f32_16x16x32_bf16 v[94:97], v[164:167], v[212:215], v[94:97]
	v_mfma_f32_16x16x32_bf16 v[78:81], v[154:157], v[216:219], v[78:81]
	v_mfma_f32_16x16x32_bf16 v[78:81], v[164:167], v[220:223], v[78:81]
	v_mfma_f32_16x16x32_bf16 v[122:125], v[168:171], v[192:195], v[122:125]
	v_mfma_f32_16x16x32_bf16 v[122:125], v[172:175], v[196:199], v[122:125]
	v_mfma_f32_16x16x32_bf16 v[106:109], v[168:171], v[200:203], v[106:109]
	v_mfma_f32_16x16x32_bf16 v[106:109], v[172:175], v[204:207], v[106:109]
	v_mfma_f32_16x16x32_bf16 v[90:93], v[168:171], v[208:211], v[90:93]
	v_mfma_f32_16x16x32_bf16 v[90:93], v[172:175], v[212:215], v[90:93]
	v_mfma_f32_16x16x32_bf16 v[74:77], v[168:171], v[216:219], v[74:77]
	v_mfma_f32_16x16x32_bf16 v[74:77], v[172:175], v[220:223], v[74:77]
	v_mfma_f32_16x16x32_bf16 v[118:121], v[176:179], v[192:195], v[118:121]
	v_mfma_f32_16x16x32_bf16 v[118:121], v[180:183], v[196:199], v[118:121]
	v_mfma_f32_16x16x32_bf16 v[102:105], v[176:179], v[200:203], v[102:105]
	v_mfma_f32_16x16x32_bf16 v[102:105], v[180:183], v[204:207], v[102:105]
	v_mfma_f32_16x16x32_bf16 v[86:89], v[176:179], v[208:211], v[86:89]
	v_mfma_f32_16x16x32_bf16 v[86:89], v[180:183], v[212:215], v[86:89]
	v_mfma_f32_16x16x32_bf16 v[70:73], v[176:179], v[216:219], v[70:73]
	v_mfma_f32_16x16x32_bf16 v[70:73], v[180:183], v[220:223], v[70:73]
	v_mfma_f32_16x16x32_bf16 v[114:117], v[184:187], v[192:195], v[114:117]
	v_mfma_f32_16x16x32_bf16 v[114:117], v[188:191], v[196:199], v[114:117]
	v_mfma_f32_16x16x32_bf16 v[98:101], v[184:187], v[200:203], v[98:101]
	v_mfma_f32_16x16x32_bf16 v[98:101], v[188:191], v[204:207], v[98:101]
	v_mfma_f32_16x16x32_bf16 v[82:85], v[184:187], v[208:211], v[82:85]
	v_mfma_f32_16x16x32_bf16 v[82:85], v[188:191], v[212:215], v[82:85]
	v_mfma_f32_16x16x32_bf16 v[66:69], v[184:187], v[216:219], v[66:69]
	v_mfma_f32_16x16x32_bf16 v[66:69], v[188:191], v[220:223], v[66:69]
	s_setprio 0
	s_barrier
	ds_read_b128 v[192:195], v163 offset:49152
	ds_read_b128 v[196:199], v163 offset:50176
	s_add_i32 m0, s33, 0x17f80
	ds_read_b128 v[200:203], v163 offset:51200
	global_load_lds_dwordx4 v134, s[74:75] offset:128
	s_add_i32 m0, s33, 0x19f80
	ds_read_b128 v[204:207], v163 offset:52224
	global_load_lds_dwordx4 v130, s[74:75] offset:128
	s_add_i32 m0, s33, 0x1bf80
	ds_read_b128 v[208:211], v163 offset:53248
	global_load_lds_dwordx4 v134, s[98:99] offset:128
	s_add_i32 m0, s33, 0x1df80
	ds_read_b128 v[212:215], v163 offset:54272
	global_load_lds_dwordx4 v130, s[98:99] offset:128
	s_add_i32 m0, s33, 0x7f80
	ds_read_b128 v[216:219], v163 offset:55296
	global_load_lds_dwordx4 v136, s[76:77] offset:128
	s_add_i32 m0, s33, 0x9f80
	ds_read_b128 v[220:223], v163 offset:56320
	global_load_lds_dwordx4 v132, s[76:77] offset:128
	s_waitcnt vmcnt(8) lgkmcnt(0)
	s_barrier
	s_setprio 1
	v_mfma_f32_16x16x32_bf16 v[62:65], v[154:157], v[192:195], v[62:65]
	v_mfma_f32_16x16x32_bf16 v[62:65], v[164:167], v[196:199], v[62:65]
	v_mfma_f32_16x16x32_bf16 v[46:49], v[154:157], v[200:203], v[46:49]
	v_mfma_f32_16x16x32_bf16 v[46:49], v[164:167], v[204:207], v[46:49]
	v_mfma_f32_16x16x32_bf16 v[30:33], v[154:157], v[208:211], v[30:33]
	v_mfma_f32_16x16x32_bf16 v[30:33], v[164:167], v[212:215], v[30:33]
	v_mfma_f32_16x16x32_bf16 v[14:17], v[154:157], v[216:219], v[14:17]
	v_mfma_f32_16x16x32_bf16 v[14:17], v[164:167], v[220:223], v[14:17]
	v_mfma_f32_16x16x32_bf16 v[58:61], v[168:171], v[192:195], v[58:61]
	v_mfma_f32_16x16x32_bf16 v[58:61], v[172:175], v[196:199], v[58:61]
	v_mfma_f32_16x16x32_bf16 v[42:45], v[168:171], v[200:203], v[42:45]
	v_mfma_f32_16x16x32_bf16 v[42:45], v[172:175], v[204:207], v[42:45]
	v_mfma_f32_16x16x32_bf16 v[26:29], v[168:171], v[208:211], v[26:29]
	v_mfma_f32_16x16x32_bf16 v[26:29], v[172:175], v[212:215], v[26:29]
	v_mfma_f32_16x16x32_bf16 v[10:13], v[168:171], v[216:219], v[10:13]
	v_mfma_f32_16x16x32_bf16 v[10:13], v[172:175], v[220:223], v[10:13]
	v_mfma_f32_16x16x32_bf16 v[54:57], v[176:179], v[192:195], v[54:57]
	v_mfma_f32_16x16x32_bf16 v[54:57], v[180:183], v[196:199], v[54:57]
	v_mfma_f32_16x16x32_bf16 v[38:41], v[176:179], v[200:203], v[38:41]
	v_mfma_f32_16x16x32_bf16 v[38:41], v[180:183], v[204:207], v[38:41]
	s_add_i32 s83, s83, 2
	v_mfma_f32_16x16x32_bf16 v[22:25], v[176:179], v[208:211], v[22:25]
	v_mfma_f32_16x16x32_bf16 v[22:25], v[180:183], v[212:215], v[22:25]
	s_add_u32 s72, s72, 0x100
	v_mfma_f32_16x16x32_bf16 v[6:9], v[176:179], v[216:219], v[6:9]
	v_mfma_f32_16x16x32_bf16 v[6:9], v[180:183], v[220:223], v[6:9]
	s_addc_u32 s73, s73, 0
	v_mfma_f32_16x16x32_bf16 v[50:53], v[184:187], v[192:195], v[50:53]
	v_mfma_f32_16x16x32_bf16 v[50:53], v[188:191], v[196:199], v[50:53]
	s_add_u32 s81, s81, 0x100
	v_mfma_f32_16x16x32_bf16 v[34:37], v[184:187], v[200:203], v[34:37]
	v_mfma_f32_16x16x32_bf16 v[34:37], v[188:191], v[204:207], v[34:37]
	s_addc_u32 s82, s82, 0
	v_mfma_f32_16x16x32_bf16 v[18:21], v[184:187], v[208:211], v[18:21]
	v_mfma_f32_16x16x32_bf16 v[18:21], v[188:191], v[212:215], v[18:21]
	s_cmp_gt_u32 s83, 61
	v_mfma_f32_16x16x32_bf16 v[2:5], v[184:187], v[216:219], v[2:5]
	v_mfma_f32_16x16x32_bf16 v[2:5], v[188:191], v[220:223], v[2:5]
	s_setprio 0
	s_barrier
	s_cbranch_scc0 .LBB0_265
	s_and_b64 vcc, exec, s[46:47]
	s_cbranch_vccz .LBB0_268
	s_barrier

.LBB0_510:
	ds_read_b128 v[146:149], v152
	ds_read_b128 v[156:159], v152 offset:1024
	ds_read_b128 v[160:163], v152 offset:2048
	ds_read_b128 v[164:167], v152 offset:3072
	ds_read_b128 v[168:171], v153
	ds_read_b128 v[172:175], v153 offset:1024
	ds_read_b128 v[176:179], v153 offset:2048
	ds_read_b128 v[180:183], v153 offset:3072
	ds_read_b128 v[184:187], v154
	ds_read_b128 v[188:191], v154 offset:1024
	ds_read_b128 v[192:195], v154 offset:2048
	ds_read_b128 v[196:199], v154 offset:3072
	ds_read_b128 v[206:209], v154 offset:4096
	ds_read_b128 v[210:213], v154 offset:5120
	s_add_i32 m0, s1, 0xc000
	ds_read_b128 v[214:217], v154 offset:6144
	global_load_lds_dwordx4 v138, s[52:53]
	s_add_i32 m0, s1, 0xe000
	ds_read_b128 v[218:221], v154 offset:7168
	global_load_lds_dwordx4 v140, s[52:53]
	s_waitcnt vmcnt(8) lgkmcnt(0)
	s_barrier
	s_setprio 1
	v_mfma_f32_16x16x32_bf16 v[126:129], v[146:149], v[184:187], v[126:129]
	v_mfma_f32_16x16x32_bf16 v[126:129], v[156:159], v[188:191], v[126:129]
	s_add_u32 s34, s52, 0xfff00080
	v_mfma_f32_16x16x32_bf16 v[110:113], v[146:149], v[192:195], v[110:113]
	v_mfma_f32_16x16x32_bf16 v[110:113], v[156:159], v[196:199], v[110:113]
	s_addc_u32 s36, s53, -1
	v_mfma_f32_16x16x32_bf16 v[94:97], v[146:149], v[206:209], v[94:97]
	v_mfma_f32_16x16x32_bf16 v[94:97], v[156:159], v[210:213], v[94:97]
	s_cmp_eq_u32 s62, 60
	v_mfma_f32_16x16x32_bf16 v[78:81], v[146:149], v[214:217], v[78:81]
	v_mfma_f32_16x16x32_bf16 v[78:81], v[156:159], v[218:221], v[78:81]
	s_cselect_b32 s67, s45, s36
	v_mfma_f32_16x16x32_bf16 v[122:125], v[160:163], v[184:187], v[122:125]
	v_mfma_f32_16x16x32_bf16 v[122:125], v[164:167], v[188:191], v[122:125]
	s_cselect_b32 s66, s51, s34
	v_mfma_f32_16x16x32_bf16 v[106:109], v[160:163], v[192:195], v[106:109]
	v_mfma_f32_16x16x32_bf16 v[106:109], v[164:167], v[196:199], v[106:109]
	s_cselect_b32 s55, s23, s61
	v_mfma_f32_16x16x32_bf16 v[90:93], v[160:163], v[206:209], v[90:93]
	v_mfma_f32_16x16x32_bf16 v[90:93], v[164:167], v[210:213], v[90:93]
	s_cselect_b32 s54, s59, s60
	v_mfma_f32_16x16x32_bf16 v[74:77], v[160:163], v[214:217], v[74:77]
	v_mfma_f32_16x16x32_bf16 v[74:77], v[164:167], v[218:221], v[74:77]
	s_add_u32 s98, s54, 0x100000
	v_mfma_f32_16x16x32_bf16 v[118:121], v[168:171], v[184:187], v[118:121]
	v_mfma_f32_16x16x32_bf16 v[118:121], v[172:175], v[188:191], v[118:121]
	s_addc_u32 s99, s55, 0
	v_mfma_f32_16x16x32_bf16 v[102:105], v[168:171], v[192:195], v[102:105]
	v_mfma_f32_16x16x32_bf16 v[102:105], v[172:175], v[196:199], v[102:105]
	s_add_u32 s100, s66, 0x100000
	v_mfma_f32_16x16x32_bf16 v[86:89], v[168:171], v[206:209], v[86:89]
	v_mfma_f32_16x16x32_bf16 v[86:89], v[172:175], v[210:213], v[86:89]
	s_addc_u32 s101, s67, 0
	v_mfma_f32_16x16x32_bf16 v[70:73], v[168:171], v[214:217], v[70:73]
	v_mfma_f32_16x16x32_bf16 v[70:73], v[172:175], v[218:221], v[70:73]
	v_mfma_f32_16x16x32_bf16 v[114:117], v[176:179], v[184:187], v[114:117]
	v_mfma_f32_16x16x32_bf16 v[114:117], v[180:183], v[188:191], v[114:117]
	v_mfma_f32_16x16x32_bf16 v[98:101], v[176:179], v[192:195], v[98:101]
	v_mfma_f32_16x16x32_bf16 v[98:101], v[180:183], v[196:199], v[98:101]
	v_mfma_f32_16x16x32_bf16 v[82:85], v[176:179], v[206:209], v[82:85]
	v_mfma_f32_16x16x32_bf16 v[82:85], v[180:183], v[210:213], v[82:85]
	v_mfma_f32_16x16x32_bf16 v[66:69], v[176:179], v[214:217], v[66:69]
	v_mfma_f32_16x16x32_bf16 v[66:69], v[180:183], v[218:221], v[66:69]
	s_setprio 0
	s_barrier
	ds_read_b128 v[184:187], v154 offset:16384
	ds_read_b128 v[188:191], v154 offset:17408
	s_add_i32 m0, s1, 0x10000
	ds_read_b128 v[192:195], v154 offset:18432
	global_load_lds_dwordx4 v132, s[54:55]
	s_add_i32 m0, s1, 0x12000
	ds_read_b128 v[196:199], v154 offset:19456
	global_load_lds_dwordx4 v136, s[54:55]
	s_add_i32 m0, s1, 0x14000
	ds_read_b128 v[206:209], v154 offset:20480
	global_load_lds_dwordx4 v132, s[98:99]
	s_add_i32 m0, s1, 0x16000
	ds_read_b128 v[210:213], v154 offset:21504
	global_load_lds_dwordx4 v136, s[98:99]
	s_mov_b32 m0, s1
	ds_read_b128 v[214:217], v154 offset:22528
	global_load_lds_dwordx4 v130, s[66:67]
	s_add_i32 m0, s1, 0x2000
	ds_read_b128 v[218:221], v154 offset:23552
	global_load_lds_dwordx4 v134, s[66:67]
	s_waitcnt vmcnt(8) lgkmcnt(0)
	s_barrier
	s_setprio 1
	v_mfma_f32_16x16x32_bf16 v[62:65], v[146:149], v[184:187], v[62:65]
	v_mfma_f32_16x16x32_bf16 v[62:65], v[156:159], v[188:191], v[62:65]
	v_mfma_f32_16x16x32_bf16 v[46:49], v[146:149], v[192:195], v[46:49]
	v_mfma_f32_16x16x32_bf16 v[46:49], v[156:159], v[196:199], v[46:49]
	v_mfma_f32_16x16x32_bf16 v[30:33], v[146:149], v[206:209], v[30:33]
	v_mfma_f32_16x16x32_bf16 v[30:33], v[156:159], v[210:213], v[30:33]
	v_mfma_f32_16x16x32_bf16 v[14:17], v[146:149], v[214:217], v[14:17]
	v_mfma_f32_16x16x32_bf16 v[14:17], v[156:159], v[218:221], v[14:17]
	v_mfma_f32_16x16x32_bf16 v[58:61], v[160:163], v[184:187], v[58:61]
	v_mfma_f32_16x16x32_bf16 v[58:61], v[164:167], v[188:191], v[58:61]
	v_mfma_f32_16x16x32_bf16 v[42:45], v[160:163], v[192:195], v[42:45]
	v_mfma_f32_16x16x32_bf16 v[42:45], v[164:167], v[196:199], v[42:45]
	v_mfma_f32_16x16x32_bf16 v[26:29], v[160:163], v[206:209], v[26:29]
	v_mfma_f32_16x16x32_bf16 v[26:29], v[164:167], v[210:213], v[26:29]
	v_mfma_f32_16x16x32_bf16 v[10:13], v[160:163], v[214:217], v[10:13]
	v_mfma_f32_16x16x32_bf16 v[10:13], v[164:167], v[218:221], v[10:13]
	v_mfma_f32_16x16x32_bf16 v[54:57], v[168:171], v[184:187], v[54:57]
	v_mfma_f32_16x16x32_bf16 v[54:57], v[172:175], v[188:191], v[54:57]
	v_mfma_f32_16x16x32_bf16 v[38:41], v[168:171], v[192:195], v[38:41]
	v_mfma_f32_16x16x32_bf16 v[38:41], v[172:175], v[196:199], v[38:41]
	v_mfma_f32_16x16x32_bf16 v[22:25], v[168:171], v[206:209], v[22:25]
	v_mfma_f32_16x16x32_bf16 v[22:25], v[172:175], v[210:213], v[22:25]
	v_mfma_f32_16x16x32_bf16 v[6:9], v[168:171], v[214:217], v[6:9]
	v_mfma_f32_16x16x32_bf16 v[6:9], v[172:175], v[218:221], v[6:9]
	v_mfma_f32_16x16x32_bf16 v[50:53], v[176:179], v[184:187], v[50:53]
	v_mfma_f32_16x16x32_bf16 v[50:53], v[180:183], v[188:191], v[50:53]
	v_mfma_f32_16x16x32_bf16 v[34:37], v[176:179], v[192:195], v[34:37]
	v_mfma_f32_16x16x32_bf16 v[34:37], v[180:183], v[196:199], v[34:37]
	v_mfma_f32_16x16x32_bf16 v[18:21], v[176:179], v[206:209], v[18:21]
	v_mfma_f32_16x16x32_bf16 v[18:21], v[180:183], v[210:213], v[18:21]
	v_mfma_f32_16x16x32_bf16 v[2:5], v[176:179], v[214:217], v[2:5]
	v_mfma_f32_16x16x32_bf16 v[2:5], v[180:183], v[218:221], v[2:5]
	s_setprio 0
	s_barrier
	ds_read_b128 v[146:149], v226
	ds_read_b128 v[156:159], v226 offset:1024
	ds_read_b128 v[160:163], v226 offset:2048
	ds_read_b128 v[164:167], v226 offset:3072
	ds_read_b128 v[168:171], v227
	ds_read_b128 v[172:175], v227 offset:1024
	ds_read_b128 v[176:179], v227 offset:2048
	ds_read_b128 v[180:183], v227 offset:3072
	ds_read_b128 v[184:187], v154 offset:32768
	ds_read_b128 v[188:191], v154 offset:33792
	ds_read_b128 v[192:195], v154 offset:34816
	ds_read_b128 v[196:199], v154 offset:35840
	ds_read_b128 v[206:209], v154 offset:36864
	ds_read_b128 v[210:213], v154 offset:37888
	s_add_i32 m0, s1, 0x4000
	ds_read_b128 v[214:217], v154 offset:38912
	global_load_lds_dwordx4 v130, s[100:101]
	s_add_i32 m0, s1, 0x6000
	ds_read_b128 v[218:221], v154 offset:39936
	global_load_lds_dwordx4 v134, s[100:101]
	s_waitcnt vmcnt(8) lgkmcnt(0)
	s_barrier
	s_setprio 1
	v_mfma_f32_16x16x32_bf16 v[126:129], v[146:149], v[184:187], v[126:129]
	v_mfma_f32_16x16x32_bf16 v[126:129], v[156:159], v[188:191], v[126:129]
	v_mfma_f32_16x16x32_bf16 v[110:113], v[146:149], v[192:195], v[110:113]
	v_mfma_f32_16x16x32_bf16 v[110:113], v[156:159], v[196:199], v[110:113]
	v_mfma_f32_16x16x32_bf16 v[94:97], v[146:149], v[206:209], v[94:97]
	v_mfma_f32_16x16x32_bf16 v[94:97], v[156:159], v[210:213], v[94:97]
	v_mfma_f32_16x16x32_bf16 v[78:81], v[146:149], v[214:217], v[78:81]
	v_mfma_f32_16x16x32_bf16 v[78:81], v[156:159], v[218:221], v[78:81]
	v_mfma_f32_16x16x32_bf16 v[122:125], v[160:163], v[184:187], v[122:125]
	v_mfma_f32_16x16x32_bf16 v[122:125], v[164:167], v[188:191], v[122:125]
	v_mfma_f32_16x16x32_bf16 v[106:109], v[160:163], v[192:195], v[106:109]
	v_mfma_f32_16x16x32_bf16 v[106:109], v[164:167], v[196:199], v[106:109]
	v_mfma_f32_16x16x32_bf16 v[90:93], v[160:163], v[206:209], v[90:93]
	v_mfma_f32_16x16x32_bf16 v[90:93], v[164:167], v[210:213], v[90:93]
	v_mfma_f32_16x16x32_bf16 v[74:77], v[160:163], v[214:217], v[74:77]
	v_mfma_f32_16x16x32_bf16 v[74:77], v[164:167], v[218:221], v[74:77]
	v_mfma_f32_16x16x32_bf16 v[118:121], v[168:171], v[184:187], v[118:121]
	v_mfma_f32_16x16x32_bf16 v[118:121], v[172:175], v[188:191], v[118:121]
	v_mfma_f32_16x16x32_bf16 v[102:105], v[168:171], v[192:195], v[102:105]
	v_mfma_f32_16x16x32_bf16 v[102:105], v[172:175], v[196:199], v[102:105]
	v_mfma_f32_16x16x32_bf16 v[86:89], v[168:171], v[206:209], v[86:89]
	v_mfma_f32_16x16x32_bf16 v[86:89], v[172:175], v[210:213], v[86:89]
	v_mfma_f32_16x16x32_bf16 v[70:73], v[168:171], v[214:217], v[70:73]
	v_mfma_f32_16x16x32_bf16 v[70:73], v[172:175], v[218:221], v[70:73]
	v_mfma_f32_16x16x32_bf16 v[114:117], v[176:179], v[184:187], v[114:117]
	v_mfma_f32_16x16x32_bf16 v[114:117], v[180:183], v[188:191], v[114:117]
	v_mfma_f32_16x16x32_bf16 v[98:101], v[176:179], v[192:195], v[98:101]
	v_mfma_f32_16x16x32_bf16 v[98:101], v[180:183], v[196:199], v[98:101]
	v_mfma_f32_16x16x32_bf16 v[82:85], v[176:179], v[206:209], v[82:85]
	v_mfma_f32_16x16x32_bf16 v[82:85], v[180:183], v[210:213], v[82:85]
	v_mfma_f32_16x16x32_bf16 v[66:69], v[176:179], v[214:217], v[66:69]
	v_mfma_f32_16x16x32_bf16 v[66:69], v[180:183], v[218:221], v[66:69]
	s_setprio 0
	s_barrier
	ds_read_b128 v[184:187], v154 offset:49152
	ds_read_b128 v[188:191], v154 offset:50176
	s_add_i32 m0, s1, 0x17f80
	ds_read_b128 v[192:195], v154 offset:51200
	global_load_lds_dwordx4 v132, s[54:55] offset:128
	s_add_i32 m0, s1, 0x19f80
	ds_read_b128 v[196:199], v154 offset:52224
	global_load_lds_dwordx4 v136, s[54:55] offset:128
	s_add_i32 m0, s1, 0x1bf80
	ds_read_b128 v[206:209], v154 offset:53248
	global_load_lds_dwordx4 v132, s[98:99] offset:128
	s_add_i32 m0, s1, 0x1df80
	ds_read_b128 v[210:213], v154 offset:54272
	global_load_lds_dwordx4 v136, s[98:99] offset:128
	s_add_i32 m0, s1, 0x7f80
	ds_read_b128 v[214:217], v154 offset:55296
	global_load_lds_dwordx4 v130, s[66:67] offset:128
	s_add_i32 m0, s1, 0x9f80
	ds_read_b128 v[218:221], v154 offset:56320
	global_load_lds_dwordx4 v134, s[66:67] offset:128
	s_waitcnt vmcnt(8) lgkmcnt(0)
	s_barrier
	s_setprio 1
	v_mfma_f32_16x16x32_bf16 v[62:65], v[146:149], v[184:187], v[62:65]
	v_mfma_f32_16x16x32_bf16 v[62:65], v[156:159], v[188:191], v[62:65]
	v_mfma_f32_16x16x32_bf16 v[46:49], v[146:149], v[192:195], v[46:49]
	v_mfma_f32_16x16x32_bf16 v[46:49], v[156:159], v[196:199], v[46:49]
	v_mfma_f32_16x16x32_bf16 v[30:33], v[146:149], v[206:209], v[30:33]
	v_mfma_f32_16x16x32_bf16 v[30:33], v[156:159], v[210:213], v[30:33]
	v_mfma_f32_16x16x32_bf16 v[14:17], v[146:149], v[214:217], v[14:17]
	v_mfma_f32_16x16x32_bf16 v[14:17], v[156:159], v[218:221], v[14:17]
	v_mfma_f32_16x16x32_bf16 v[58:61], v[160:163], v[184:187], v[58:61]
	v_mfma_f32_16x16x32_bf16 v[58:61], v[164:167], v[188:191], v[58:61]
	v_mfma_f32_16x16x32_bf16 v[42:45], v[160:163], v[192:195], v[42:45]
	v_mfma_f32_16x16x32_bf16 v[42:45], v[164:167], v[196:199], v[42:45]
	v_mfma_f32_16x16x32_bf16 v[26:29], v[160:163], v[206:209], v[26:29]
	v_mfma_f32_16x16x32_bf16 v[26:29], v[164:167], v[210:213], v[26:29]
	v_mfma_f32_16x16x32_bf16 v[10:13], v[160:163], v[214:217], v[10:13]
	v_mfma_f32_16x16x32_bf16 v[10:13], v[164:167], v[218:221], v[10:13]
	v_mfma_f32_16x16x32_bf16 v[54:57], v[168:171], v[184:187], v[54:57]
	v_mfma_f32_16x16x32_bf16 v[54:57], v[172:175], v[188:191], v[54:57]
	v_mfma_f32_16x16x32_bf16 v[38:41], v[168:171], v[192:195], v[38:41]
	v_mfma_f32_16x16x32_bf16 v[38:41], v[172:175], v[196:199], v[38:41]
	s_add_i32 s62, s62, 2
	v_mfma_f32_16x16x32_bf16 v[22:25], v[168:171], v[206:209], v[22:25]
	v_mfma_f32_16x16x32_bf16 v[22:25], v[172:175], v[210:213], v[22:25]
	s_add_u32 s60, s60, 0x100
	v_mfma_f32_16x16x32_bf16 v[6:9], v[168:171], v[214:217], v[6:9]
	v_mfma_f32_16x16x32_bf16 v[6:9], v[172:175], v[218:221], v[6:9]
	s_addc_u32 s61, s61, 0
	v_mfma_f32_16x16x32_bf16 v[50:53], v[176:179], v[184:187], v[50:53]
	v_mfma_f32_16x16x32_bf16 v[50:53], v[180:183], v[188:191], v[50:53]
	s_add_u32 s52, s52, 0x100
	v_mfma_f32_16x16x32_bf16 v[34:37], v[176:179], v[192:195], v[34:37]
	v_mfma_f32_16x16x32_bf16 v[34:37], v[180:183], v[196:199], v[34:37]
	s_addc_u32 s53, s53, 0
	v_mfma_f32_16x16x32_bf16 v[18:21], v[176:179], v[206:209], v[18:21]
	v_mfma_f32_16x16x32_bf16 v[18:21], v[180:183], v[210:213], v[18:21]
	s_cmp_gt_u32 s62, 61
	v_mfma_f32_16x16x32_bf16 v[2:5], v[176:179], v[214:217], v[2:5]
	v_mfma_f32_16x16x32_bf16 v[2:5], v[180:183], v[218:221], v[2:5]
	s_setprio 0
	s_barrier
	s_cbranch_scc0 .LBB0_510
	s_and_b64 vcc, exec, s[20:21]
	s_cbranch_vccz .LBB0_513
	s_barrier

.LBB0_651:
	ds_read_b128 v[130:133], v210
	ds_read_b128 v[134:137], v210 offset:1024
	ds_read_b128 v[138:141], v210 offset:2048
	ds_read_b128 v[142:145], v210 offset:3072
	ds_read_b128 v[146:149], v211
	ds_read_b128 v[150:153], v211 offset:1024
	ds_read_b128 v[154:157], v211 offset:2048
	ds_read_b128 v[158:161], v211 offset:3072
	ds_read_b128 v[162:165], v212
	ds_read_b128 v[166:169], v212 offset:1024
	ds_read_b128 v[188:191], v212 offset:2048
	ds_read_b128 v[192:195], v212 offset:3072
	ds_read_b128 v[196:199], v212 offset:4096
	ds_read_b128 v[214:217], v212 offset:5120
	s_add_i32 m0, s39, 0xc000
	ds_read_b128 v[218:221], v212 offset:6144
	global_load_lds_dwordx4 v180, s[88:89]
	s_add_i32 m0, s39, 0xe000
	ds_read_b128 v[222:225], v212 offset:7168
	global_load_lds_dwordx4 v182, s[88:89]
	s_waitcnt vmcnt(8) lgkmcnt(0)
	s_barrier
	s_setprio 1
	v_mfma_f32_16x16x32_bf16 v[126:129], v[130:133], v[162:165], v[126:129]
	v_mfma_f32_16x16x32_bf16 v[126:129], v[134:137], v[166:169], v[126:129]
	s_add_u32 s90, s88, 0x100
	v_mfma_f32_16x16x32_bf16 v[122:125], v[130:133], v[188:191], v[122:125]
	v_mfma_f32_16x16x32_bf16 v[122:125], v[134:137], v[192:195], v[122:125]
	s_addc_u32 s91, s89, 0
	v_mfma_f32_16x16x32_bf16 v[110:113], v[130:133], v[196:199], v[110:113]
	v_mfma_f32_16x16x32_bf16 v[110:113], v[134:137], v[214:217], v[110:113]
	s_cmp_eq_u32 s66, 60
	v_mfma_f32_16x16x32_bf16 v[106:109], v[130:133], v[218:221], v[106:109]
	v_mfma_f32_16x16x32_bf16 v[106:109], v[134:137], v[222:225], v[106:109]
	s_cselect_b32 s95, s79, s91
	v_mfma_f32_16x16x32_bf16 v[62:65], v[138:141], v[162:165], v[62:65]
	v_mfma_f32_16x16x32_bf16 v[62:65], v[142:145], v[166:169], v[62:65]
	s_cselect_b32 s94, s85, s90
	v_mfma_f32_16x16x32_bf16 v[58:61], v[138:141], v[188:191], v[58:61]
	v_mfma_f32_16x16x32_bf16 v[58:61], v[142:145], v[192:195], v[58:61]
	s_cselect_b32 s93, s77, vcc_hi
	v_mfma_f32_16x16x32_bf16 v[50:53], v[138:141], v[196:199], v[50:53]
	v_mfma_f32_16x16x32_bf16 v[50:53], v[142:145], v[214:217], v[50:53]
	s_cselect_b32 s92, s87, vcc_lo
	v_mfma_f32_16x16x32_bf16 v[42:45], v[138:141], v[218:221], v[42:45]
	v_mfma_f32_16x16x32_bf16 v[42:45], v[142:145], v[222:225], v[42:45]
	s_add_u32 s98, s92, 0x100000
	v_mfma_f32_16x16x32_bf16 v[118:121], v[146:149], v[162:165], v[118:121]
	v_mfma_f32_16x16x32_bf16 v[118:121], v[150:153], v[166:169], v[118:121]
	s_addc_u32 s99, s93, 0
	v_mfma_f32_16x16x32_bf16 v[114:117], v[146:149], v[188:191], v[114:117]
	v_mfma_f32_16x16x32_bf16 v[114:117], v[150:153], v[192:195], v[114:117]
	s_add_u32 s100, s94, 0x100000
	v_mfma_f32_16x16x32_bf16 v[102:105], v[146:149], v[196:199], v[102:105]
	v_mfma_f32_16x16x32_bf16 v[102:105], v[150:153], v[214:217], v[102:105]
	s_addc_u32 s101, s95, 0
	v_mfma_f32_16x16x32_bf16 v[98:101], v[146:149], v[218:221], v[98:101]
	v_mfma_f32_16x16x32_bf16 v[98:101], v[150:153], v[222:225], v[98:101]
	v_mfma_f32_16x16x32_bf16 v[54:57], v[154:157], v[162:165], v[54:57]
	v_mfma_f32_16x16x32_bf16 v[54:57], v[158:161], v[166:169], v[54:57]
	v_mfma_f32_16x16x32_bf16 v[46:49], v[154:157], v[188:191], v[46:49]
	v_mfma_f32_16x16x32_bf16 v[46:49], v[158:161], v[192:195], v[46:49]
	v_mfma_f32_16x16x32_bf16 v[38:41], v[154:157], v[196:199], v[38:41]
	v_mfma_f32_16x16x32_bf16 v[38:41], v[158:161], v[214:217], v[38:41]
	v_mfma_f32_16x16x32_bf16 v[34:37], v[154:157], v[218:221], v[34:37]
	v_mfma_f32_16x16x32_bf16 v[34:37], v[158:161], v[222:225], v[34:37]
	s_setprio 0
	s_barrier
	ds_read_b128 v[162:165], v212 offset:16384
	ds_read_b128 v[166:169], v212 offset:17408
	s_add_i32 m0, s39, 0x10000
	ds_read_b128 v[188:191], v212 offset:18432
	global_load_lds_dwordx4 v172, s[92:93]
	s_add_i32 m0, s39, 0x12000
	ds_read_b128 v[192:195], v212 offset:19456
	global_load_lds_dwordx4 v176, s[92:93]
	s_add_i32 m0, s39, 0x14000
	ds_read_b128 v[196:199], v212 offset:20480
	global_load_lds_dwordx4 v172, s[98:99]
	s_add_i32 m0, s39, 0x16000
	ds_read_b128 v[214:217], v212 offset:21504
	global_load_lds_dwordx4 v176, s[98:99]
	s_mov_b32 m0, s39
	ds_read_b128 v[218:221], v212 offset:22528
	global_load_lds_dwordx4 v170, s[94:95]
	s_add_i32 m0, s39, 0x2000
	ds_read_b128 v[222:225], v212 offset:23552
	global_load_lds_dwordx4 v174, s[94:95]
	s_waitcnt vmcnt(8) lgkmcnt(0)
	s_barrier
	s_setprio 1
	v_mfma_f32_16x16x32_bf16 v[94:97], v[130:133], v[162:165], v[94:97]
	v_mfma_f32_16x16x32_bf16 v[94:97], v[134:137], v[166:169], v[94:97]
	v_mfma_f32_16x16x32_bf16 v[90:93], v[130:133], v[188:191], v[90:93]
	v_mfma_f32_16x16x32_bf16 v[90:93], v[134:137], v[192:195], v[90:93]
	v_mfma_f32_16x16x32_bf16 v[82:85], v[130:133], v[196:199], v[82:85]
	v_mfma_f32_16x16x32_bf16 v[82:85], v[134:137], v[214:217], v[82:85]
	v_mfma_f32_16x16x32_bf16 v[74:77], v[130:133], v[218:221], v[74:77]
	v_mfma_f32_16x16x32_bf16 v[74:77], v[134:137], v[222:225], v[74:77]
	v_mfma_f32_16x16x32_bf16 v[30:33], v[138:141], v[162:165], v[30:33]
	v_mfma_f32_16x16x32_bf16 v[30:33], v[142:145], v[166:169], v[30:33]
	v_mfma_f32_16x16x32_bf16 v[26:29], v[138:141], v[188:191], v[26:29]
	v_mfma_f32_16x16x32_bf16 v[26:29], v[142:145], v[192:195], v[26:29]
	v_mfma_f32_16x16x32_bf16 v[18:21], v[138:141], v[196:199], v[18:21]
	v_mfma_f32_16x16x32_bf16 v[18:21], v[142:145], v[214:217], v[18:21]
	v_mfma_f32_16x16x32_bf16 v[10:13], v[138:141], v[218:221], v[10:13]
	v_mfma_f32_16x16x32_bf16 v[10:13], v[142:145], v[222:225], v[10:13]
	v_mfma_f32_16x16x32_bf16 v[86:89], v[146:149], v[162:165], v[86:89]
	v_mfma_f32_16x16x32_bf16 v[86:89], v[150:153], v[166:169], v[86:89]
	v_mfma_f32_16x16x32_bf16 v[78:81], v[146:149], v[188:191], v[78:81]
	v_mfma_f32_16x16x32_bf16 v[78:81], v[150:153], v[192:195], v[78:81]
	v_mfma_f32_16x16x32_bf16 v[70:73], v[146:149], v[196:199], v[70:73]
	v_mfma_f32_16x16x32_bf16 v[70:73], v[150:153], v[214:217], v[70:73]
	v_mfma_f32_16x16x32_bf16 v[66:69], v[146:149], v[218:221], v[66:69]
	v_mfma_f32_16x16x32_bf16 v[66:69], v[150:153], v[222:225], v[66:69]
	v_mfma_f32_16x16x32_bf16 v[22:25], v[154:157], v[162:165], v[22:25]
	v_mfma_f32_16x16x32_bf16 v[22:25], v[158:161], v[166:169], v[22:25]
	v_mfma_f32_16x16x32_bf16 v[14:17], v[154:157], v[188:191], v[14:17]
	v_mfma_f32_16x16x32_bf16 v[14:17], v[158:161], v[192:195], v[14:17]
	v_mfma_f32_16x16x32_bf16 v[6:9], v[154:157], v[196:199], v[6:9]
	v_mfma_f32_16x16x32_bf16 v[6:9], v[158:161], v[214:217], v[6:9]
	v_mfma_f32_16x16x32_bf16 v[2:5], v[154:157], v[218:221], v[2:5]
	v_mfma_f32_16x16x32_bf16 v[2:5], v[158:161], v[222:225], v[2:5]
	s_setprio 0
	s_barrier
	ds_read_b128 v[130:133], v226
	ds_read_b128 v[134:137], v226 offset:1024
	ds_read_b128 v[138:141], v226 offset:2048
	ds_read_b128 v[142:145], v226 offset:3072
	ds_read_b128 v[146:149], v227
	ds_read_b128 v[150:153], v227 offset:1024
	ds_read_b128 v[154:157], v227 offset:2048
	ds_read_b128 v[158:161], v227 offset:3072
	ds_read_b128 v[162:165], v212 offset:32768
	ds_read_b128 v[166:169], v212 offset:33792
	ds_read_b128 v[188:191], v212 offset:34816
	ds_read_b128 v[192:195], v212 offset:35840
	ds_read_b128 v[196:199], v212 offset:36864
	ds_read_b128 v[214:217], v212 offset:37888
	s_add_i32 m0, s39, 0x4000
	ds_read_b128 v[218:221], v212 offset:38912
	global_load_lds_dwordx4 v170, s[100:101]
	s_add_i32 m0, s39, 0x6000
	ds_read_b128 v[222:225], v212 offset:39936
	global_load_lds_dwordx4 v174, s[100:101]
	s_waitcnt vmcnt(8) lgkmcnt(0)
	s_barrier
	s_setprio 1
	v_mfma_f32_16x16x32_bf16 v[126:129], v[130:133], v[162:165], v[126:129]
	v_mfma_f32_16x16x32_bf16 v[126:129], v[134:137], v[166:169], v[126:129]
	v_mfma_f32_16x16x32_bf16 v[122:125], v[130:133], v[188:191], v[122:125]
	v_mfma_f32_16x16x32_bf16 v[122:125], v[134:137], v[192:195], v[122:125]
	v_mfma_f32_16x16x32_bf16 v[110:113], v[130:133], v[196:199], v[110:113]
	v_mfma_f32_16x16x32_bf16 v[110:113], v[134:137], v[214:217], v[110:113]
	v_mfma_f32_16x16x32_bf16 v[106:109], v[130:133], v[218:221], v[106:109]
	v_mfma_f32_16x16x32_bf16 v[106:109], v[134:137], v[222:225], v[106:109]
	v_mfma_f32_16x16x32_bf16 v[62:65], v[138:141], v[162:165], v[62:65]
	v_mfma_f32_16x16x32_bf16 v[62:65], v[142:145], v[166:169], v[62:65]
	v_mfma_f32_16x16x32_bf16 v[58:61], v[138:141], v[188:191], v[58:61]
	v_mfma_f32_16x16x32_bf16 v[58:61], v[142:145], v[192:195], v[58:61]
	v_mfma_f32_16x16x32_bf16 v[50:53], v[138:141], v[196:199], v[50:53]
	v_mfma_f32_16x16x32_bf16 v[50:53], v[142:145], v[214:217], v[50:53]
	v_mfma_f32_16x16x32_bf16 v[42:45], v[138:141], v[218:221], v[42:45]
	v_mfma_f32_16x16x32_bf16 v[42:45], v[142:145], v[222:225], v[42:45]
	v_mfma_f32_16x16x32_bf16 v[118:121], v[146:149], v[162:165], v[118:121]
	v_mfma_f32_16x16x32_bf16 v[118:121], v[150:153], v[166:169], v[118:121]
	v_mfma_f32_16x16x32_bf16 v[114:117], v[146:149], v[188:191], v[114:117]
	v_mfma_f32_16x16x32_bf16 v[114:117], v[150:153], v[192:195], v[114:117]
	v_mfma_f32_16x16x32_bf16 v[102:105], v[146:149], v[196:199], v[102:105]
	v_mfma_f32_16x16x32_bf16 v[102:105], v[150:153], v[214:217], v[102:105]
	v_mfma_f32_16x16x32_bf16 v[98:101], v[146:149], v[218:221], v[98:101]
	v_mfma_f32_16x16x32_bf16 v[98:101], v[150:153], v[222:225], v[98:101]
	v_mfma_f32_16x16x32_bf16 v[54:57], v[154:157], v[162:165], v[54:57]
	v_mfma_f32_16x16x32_bf16 v[54:57], v[158:161], v[166:169], v[54:57]
	v_mfma_f32_16x16x32_bf16 v[46:49], v[154:157], v[188:191], v[46:49]
	v_mfma_f32_16x16x32_bf16 v[46:49], v[158:161], v[192:195], v[46:49]
	v_mfma_f32_16x16x32_bf16 v[38:41], v[154:157], v[196:199], v[38:41]
	v_mfma_f32_16x16x32_bf16 v[38:41], v[158:161], v[214:217], v[38:41]
	v_mfma_f32_16x16x32_bf16 v[34:37], v[154:157], v[218:221], v[34:37]
	v_mfma_f32_16x16x32_bf16 v[34:37], v[158:161], v[222:225], v[34:37]
	s_setprio 0
	s_barrier
	ds_read_b128 v[162:165], v212 offset:49152
	ds_read_b128 v[166:169], v212 offset:50176
	s_add_i32 m0, s39, 0x17f80
	ds_read_b128 v[188:191], v212 offset:51200
	global_load_lds_dwordx4 v172, s[92:93] offset:128
	s_add_i32 m0, s39, 0x19f80
	ds_read_b128 v[192:195], v212 offset:52224
	global_load_lds_dwordx4 v176, s[92:93] offset:128
	s_add_i32 m0, s39, 0x1bf80
	ds_read_b128 v[196:199], v212 offset:53248
	global_load_lds_dwordx4 v172, s[98:99] offset:128
	s_add_i32 m0, s39, 0x1df80
	ds_read_b128 v[214:217], v212 offset:54272
	global_load_lds_dwordx4 v176, s[98:99] offset:128
	s_add_i32 m0, s39, 0x7f80
	ds_read_b128 v[218:221], v212 offset:55296
	global_load_lds_dwordx4 v170, s[94:95] offset:128
	s_add_i32 m0, s39, 0x9f80
	ds_read_b128 v[222:225], v212 offset:56320
	global_load_lds_dwordx4 v174, s[94:95] offset:128
	s_waitcnt vmcnt(8) lgkmcnt(0)
	s_barrier
	s_setprio 1
	v_mfma_f32_16x16x32_bf16 v[94:97], v[130:133], v[162:165], v[94:97]
	v_mfma_f32_16x16x32_bf16 v[94:97], v[134:137], v[166:169], v[94:97]
	v_mfma_f32_16x16x32_bf16 v[90:93], v[130:133], v[188:191], v[90:93]
	v_mfma_f32_16x16x32_bf16 v[90:93], v[134:137], v[192:195], v[90:93]
	v_mfma_f32_16x16x32_bf16 v[82:85], v[130:133], v[196:199], v[82:85]
	v_mfma_f32_16x16x32_bf16 v[82:85], v[134:137], v[214:217], v[82:85]
	v_mfma_f32_16x16x32_bf16 v[74:77], v[130:133], v[218:221], v[74:77]
	v_mfma_f32_16x16x32_bf16 v[74:77], v[134:137], v[222:225], v[74:77]
	v_mfma_f32_16x16x32_bf16 v[30:33], v[138:141], v[162:165], v[30:33]
	v_mfma_f32_16x16x32_bf16 v[30:33], v[142:145], v[166:169], v[30:33]
	v_mfma_f32_16x16x32_bf16 v[26:29], v[138:141], v[188:191], v[26:29]
	v_mfma_f32_16x16x32_bf16 v[26:29], v[142:145], v[192:195], v[26:29]
	v_mfma_f32_16x16x32_bf16 v[18:21], v[138:141], v[196:199], v[18:21]
	v_mfma_f32_16x16x32_bf16 v[18:21], v[142:145], v[214:217], v[18:21]
	v_mfma_f32_16x16x32_bf16 v[10:13], v[138:141], v[218:221], v[10:13]
	v_mfma_f32_16x16x32_bf16 v[10:13], v[142:145], v[222:225], v[10:13]
	v_mfma_f32_16x16x32_bf16 v[86:89], v[146:149], v[162:165], v[86:89]
	v_mfma_f32_16x16x32_bf16 v[86:89], v[150:153], v[166:169], v[86:89]
	v_mfma_f32_16x16x32_bf16 v[78:81], v[146:149], v[188:191], v[78:81]
	v_mfma_f32_16x16x32_bf16 v[78:81], v[150:153], v[192:195], v[78:81]
	v_mfma_f32_16x16x32_bf16 v[70:73], v[146:149], v[196:199], v[70:73]
	v_mfma_f32_16x16x32_bf16 v[70:73], v[150:153], v[214:217], v[70:73]
	s_add_i32 s66, s66, 2
	v_mfma_f32_16x16x32_bf16 v[66:69], v[146:149], v[218:221], v[66:69]
	v_mfma_f32_16x16x32_bf16 v[66:69], v[150:153], v[222:225], v[66:69]
	s_add_u32 vcc_lo, vcc_lo, 0x100
	v_mfma_f32_16x16x32_bf16 v[22:25], v[154:157], v[162:165], v[22:25]
	v_mfma_f32_16x16x32_bf16 v[22:25], v[158:161], v[166:169], v[22:25]
	s_addc_u32 vcc_hi, vcc_hi, 0
	v_mfma_f32_16x16x32_bf16 v[14:17], v[154:157], v[188:191], v[14:17]
	v_mfma_f32_16x16x32_bf16 v[14:17], v[158:161], v[192:195], v[14:17]
	s_mov_b64 s[88:89], s[90:91]
	v_mfma_f32_16x16x32_bf16 v[6:9], v[154:157], v[196:199], v[6:9]
	v_mfma_f32_16x16x32_bf16 v[6:9], v[158:161], v[214:217], v[6:9]
	s_cmp_gt_u32 s66, 61
	v_mfma_f32_16x16x32_bf16 v[2:5], v[154:157], v[218:221], v[2:5]
	v_mfma_f32_16x16x32_bf16 v[2:5], v[158:161], v[222:225], v[2:5]
	s_setprio 0
	s_barrier
	s_cbranch_scc0 .LBB0_651
	s_and_b64 vcc, exec, s[36:37]
	s_cbranch_vccz .LBB0_654
	s_barrier

.LBB0_834:
	ds_read_b128 v[146:149], v152
	ds_read_b128 v[156:159], v152 offset:1024
	ds_read_b128 v[160:163], v152 offset:2048
	ds_read_b128 v[164:167], v152 offset:3072
	ds_read_b128 v[168:171], v153
	ds_read_b128 v[172:175], v153 offset:1024
	ds_read_b128 v[176:179], v153 offset:2048
	ds_read_b128 v[180:183], v153 offset:3072
	ds_read_b128 v[184:187], v154
	ds_read_b128 v[188:191], v154 offset:1024
	ds_read_b128 v[192:195], v154 offset:2048
	ds_read_b128 v[196:199], v154 offset:3072
	ds_read_b128 v[206:209], v154 offset:4096
	ds_read_b128 v[210:213], v154 offset:5120
	s_add_i32 m0, s1, 0xc000
	ds_read_b128 v[214:217], v154 offset:6144
	global_load_lds_dwordx4 v138, s[42:43]
	s_add_i32 m0, s1, 0xe000
	ds_read_b128 v[218:221], v154 offset:7168
	global_load_lds_dwordx4 v140, s[42:43]
	s_waitcnt vmcnt(8) lgkmcnt(0)
	s_barrier
	s_setprio 1
	v_mfma_f32_16x16x32_bf16 v[126:129], v[146:149], v[184:187], v[126:129]
	v_mfma_f32_16x16x32_bf16 v[126:129], v[156:159], v[188:191], v[126:129]
	s_add_u32 s34, s42, 0x1fc000
	s_addc_u32 s44, s43, 0
	v_mfma_f32_16x16x32_bf16 v[110:113], v[146:149], v[192:195], v[110:113]
	v_mfma_f32_16x16x32_bf16 v[110:113], v[156:159], v[196:199], v[110:113]
	s_cmpk_eq_i32 s61, 0xa8
	s_cselect_b32 s48, s41, s34
	v_mfma_f32_16x16x32_bf16 v[94:97], v[146:149], v[206:209], v[94:97]
	v_mfma_f32_16x16x32_bf16 v[94:97], v[156:159], v[210:213], v[94:97]
	s_cselect_b32 s49, s23, s44
	s_cselect_b32 s47, s21, s60
	v_mfma_f32_16x16x32_bf16 v[78:81], v[146:149], v[214:217], v[78:81]
	v_mfma_f32_16x16x32_bf16 v[78:81], v[156:159], v[218:221], v[78:81]
	s_cselect_b32 s46, s58, s59
	s_add_u32 s44, s48, 0x200000
	v_mfma_f32_16x16x32_bf16 v[122:125], v[160:163], v[184:187], v[122:125]
	v_mfma_f32_16x16x32_bf16 v[122:125], v[164:167], v[188:191], v[122:125]
	s_addc_u32 s45, s49, 0
	s_add_u32 s62, s46, 0x4000
	v_mfma_f32_16x16x32_bf16 v[106:109], v[160:163], v[192:195], v[106:109]
	v_mfma_f32_16x16x32_bf16 v[106:109], v[164:167], v[196:199], v[106:109]
	s_addc_u32 s63, s47, 0
	s_add_u32 s100, s48, 0x4000
	v_mfma_f32_16x16x32_bf16 v[90:93], v[160:163], v[206:209], v[90:93]
	v_mfma_f32_16x16x32_bf16 v[90:93], v[164:167], v[210:213], v[90:93]
	s_addc_u32 s101, s49, 0
	s_add_u32 s98, s46, 0x80000
	v_mfma_f32_16x16x32_bf16 v[74:77], v[160:163], v[214:217], v[74:77]
	v_mfma_f32_16x16x32_bf16 v[74:77], v[164:167], v[218:221], v[74:77]
	s_addc_u32 s99, s47, 0
	s_add_u32 s24, s46, 0x84000
	v_mfma_f32_16x16x32_bf16 v[118:121], v[168:171], v[184:187], v[118:121]
	v_mfma_f32_16x16x32_bf16 v[118:121], v[172:175], v[188:191], v[118:121]
	s_addc_u32 s25, s47, 0
	v_mfma_f32_16x16x32_bf16 v[102:105], v[168:171], v[192:195], v[102:105]
	v_mfma_f32_16x16x32_bf16 v[102:105], v[172:175], v[196:199], v[102:105]
	v_mfma_f32_16x16x32_bf16 v[86:89], v[168:171], v[206:209], v[86:89]
	v_mfma_f32_16x16x32_bf16 v[86:89], v[172:175], v[210:213], v[86:89]
	v_mfma_f32_16x16x32_bf16 v[70:73], v[168:171], v[214:217], v[70:73]
	v_mfma_f32_16x16x32_bf16 v[70:73], v[172:175], v[218:221], v[70:73]
	v_mfma_f32_16x16x32_bf16 v[114:117], v[176:179], v[184:187], v[114:117]
	v_mfma_f32_16x16x32_bf16 v[114:117], v[180:183], v[188:191], v[114:117]
	v_mfma_f32_16x16x32_bf16 v[98:101], v[176:179], v[192:195], v[98:101]
	v_mfma_f32_16x16x32_bf16 v[98:101], v[180:183], v[196:199], v[98:101]
	v_mfma_f32_16x16x32_bf16 v[82:85], v[176:179], v[206:209], v[82:85]
	v_mfma_f32_16x16x32_bf16 v[82:85], v[180:183], v[210:213], v[82:85]
	v_mfma_f32_16x16x32_bf16 v[66:69], v[176:179], v[214:217], v[66:69]
	v_mfma_f32_16x16x32_bf16 v[66:69], v[180:183], v[218:221], v[66:69]
	s_setprio 0
	s_barrier
	ds_read_b128 v[184:187], v154 offset:16384
	ds_read_b128 v[188:191], v154 offset:17408
	s_add_i32 m0, s1, 0x10000
	ds_read_b128 v[192:195], v154 offset:18432
	global_load_lds_dwordx4 v132, s[46:47]
	s_add_i32 m0, s1, 0x12000
	ds_read_b128 v[196:199], v154 offset:19456
	global_load_lds_dwordx4 v136, s[46:47]
	s_add_i32 m0, s1, 0x14000
	ds_read_b128 v[206:209], v154 offset:20480
	global_load_lds_dwordx4 v132, s[62:63]
	s_add_i32 m0, s1, 0x16000
	ds_read_b128 v[210:213], v154 offset:21504
	global_load_lds_dwordx4 v136, s[62:63]
	s_mov_b32 m0, s1
	ds_read_b128 v[214:217], v154 offset:22528
	global_load_lds_dwordx4 v130, s[48:49]
	s_add_i32 m0, s1, 0x2000
	ds_read_b128 v[218:221], v154 offset:23552
	global_load_lds_dwordx4 v134, s[48:49]
	s_waitcnt vmcnt(8) lgkmcnt(0)
	s_barrier
	s_setprio 1
	v_mfma_f32_16x16x32_bf16 v[62:65], v[146:149], v[184:187], v[62:65]
	v_mfma_f32_16x16x32_bf16 v[62:65], v[156:159], v[188:191], v[62:65]
	v_mfma_f32_16x16x32_bf16 v[46:49], v[146:149], v[192:195], v[46:49]
	v_mfma_f32_16x16x32_bf16 v[46:49], v[156:159], v[196:199], v[46:49]
	v_mfma_f32_16x16x32_bf16 v[30:33], v[146:149], v[206:209], v[30:33]
	v_mfma_f32_16x16x32_bf16 v[30:33], v[156:159], v[210:213], v[30:33]
	v_mfma_f32_16x16x32_bf16 v[14:17], v[146:149], v[214:217], v[14:17]
	v_mfma_f32_16x16x32_bf16 v[14:17], v[156:159], v[218:221], v[14:17]
	v_mfma_f32_16x16x32_bf16 v[58:61], v[160:163], v[184:187], v[58:61]
	v_mfma_f32_16x16x32_bf16 v[58:61], v[164:167], v[188:191], v[58:61]
	v_mfma_f32_16x16x32_bf16 v[42:45], v[160:163], v[192:195], v[42:45]
	v_mfma_f32_16x16x32_bf16 v[42:45], v[164:167], v[196:199], v[42:45]
	v_mfma_f32_16x16x32_bf16 v[26:29], v[160:163], v[206:209], v[26:29]
	v_mfma_f32_16x16x32_bf16 v[26:29], v[164:167], v[210:213], v[26:29]
	v_mfma_f32_16x16x32_bf16 v[10:13], v[160:163], v[214:217], v[10:13]
	v_mfma_f32_16x16x32_bf16 v[10:13], v[164:167], v[218:221], v[10:13]
	v_mfma_f32_16x16x32_bf16 v[54:57], v[168:171], v[184:187], v[54:57]
	v_mfma_f32_16x16x32_bf16 v[54:57], v[172:175], v[188:191], v[54:57]
	v_mfma_f32_16x16x32_bf16 v[38:41], v[168:171], v[192:195], v[38:41]
	v_mfma_f32_16x16x32_bf16 v[38:41], v[172:175], v[196:199], v[38:41]
	v_mfma_f32_16x16x32_bf16 v[22:25], v[168:171], v[206:209], v[22:25]
	v_mfma_f32_16x16x32_bf16 v[22:25], v[172:175], v[210:213], v[22:25]
	v_mfma_f32_16x16x32_bf16 v[6:9], v[168:171], v[214:217], v[6:9]
	v_mfma_f32_16x16x32_bf16 v[6:9], v[172:175], v[218:221], v[6:9]
	v_mfma_f32_16x16x32_bf16 v[50:53], v[176:179], v[184:187], v[50:53]
	v_mfma_f32_16x16x32_bf16 v[50:53], v[180:183], v[188:191], v[50:53]
	v_mfma_f32_16x16x32_bf16 v[34:37], v[176:179], v[192:195], v[34:37]
	v_mfma_f32_16x16x32_bf16 v[34:37], v[180:183], v[196:199], v[34:37]
	v_mfma_f32_16x16x32_bf16 v[18:21], v[176:179], v[206:209], v[18:21]
	v_mfma_f32_16x16x32_bf16 v[18:21], v[180:183], v[210:213], v[18:21]
	v_mfma_f32_16x16x32_bf16 v[2:5], v[176:179], v[214:217], v[2:5]
	v_mfma_f32_16x16x32_bf16 v[2:5], v[180:183], v[218:221], v[2:5]
	s_setprio 0
	s_barrier
	ds_read_b128 v[146:149], v226
	ds_read_b128 v[156:159], v226 offset:1024
	ds_read_b128 v[160:163], v226 offset:2048
	ds_read_b128 v[164:167], v226 offset:3072
	ds_read_b128 v[168:171], v227
	ds_read_b128 v[172:175], v227 offset:1024
	ds_read_b128 v[176:179], v227 offset:2048
	ds_read_b128 v[180:183], v227 offset:3072
	ds_read_b128 v[184:187], v154 offset:32768
	ds_read_b128 v[188:191], v154 offset:33792
	ds_read_b128 v[192:195], v154 offset:34816
	ds_read_b128 v[196:199], v154 offset:35840
	ds_read_b128 v[206:209], v154 offset:36864
	ds_read_b128 v[210:213], v154 offset:37888
	s_add_i32 m0, s1, 0x4000
	ds_read_b128 v[214:217], v154 offset:38912
	global_load_lds_dwordx4 v130, s[100:101]
	s_add_i32 m0, s1, 0x6000
	ds_read_b128 v[218:221], v154 offset:39936
	global_load_lds_dwordx4 v134, s[100:101]
	s_waitcnt vmcnt(8) lgkmcnt(0)
	s_barrier
	s_setprio 1
	v_mfma_f32_16x16x32_bf16 v[126:129], v[146:149], v[184:187], v[126:129]
	v_mfma_f32_16x16x32_bf16 v[126:129], v[156:159], v[188:191], v[126:129]
	v_mfma_f32_16x16x32_bf16 v[110:113], v[146:149], v[192:195], v[110:113]
	v_mfma_f32_16x16x32_bf16 v[110:113], v[156:159], v[196:199], v[110:113]
	v_mfma_f32_16x16x32_bf16 v[94:97], v[146:149], v[206:209], v[94:97]
	v_mfma_f32_16x16x32_bf16 v[94:97], v[156:159], v[210:213], v[94:97]
	v_mfma_f32_16x16x32_bf16 v[78:81], v[146:149], v[214:217], v[78:81]
	v_mfma_f32_16x16x32_bf16 v[78:81], v[156:159], v[218:221], v[78:81]
	v_mfma_f32_16x16x32_bf16 v[122:125], v[160:163], v[184:187], v[122:125]
	v_mfma_f32_16x16x32_bf16 v[122:125], v[164:167], v[188:191], v[122:125]
	v_mfma_f32_16x16x32_bf16 v[106:109], v[160:163], v[192:195], v[106:109]
	v_mfma_f32_16x16x32_bf16 v[106:109], v[164:167], v[196:199], v[106:109]
	v_mfma_f32_16x16x32_bf16 v[90:93], v[160:163], v[206:209], v[90:93]
	v_mfma_f32_16x16x32_bf16 v[90:93], v[164:167], v[210:213], v[90:93]
	v_mfma_f32_16x16x32_bf16 v[74:77], v[160:163], v[214:217], v[74:77]
	v_mfma_f32_16x16x32_bf16 v[74:77], v[164:167], v[218:221], v[74:77]
	v_mfma_f32_16x16x32_bf16 v[118:121], v[168:171], v[184:187], v[118:121]
	v_mfma_f32_16x16x32_bf16 v[118:121], v[172:175], v[188:191], v[118:121]
	v_mfma_f32_16x16x32_bf16 v[102:105], v[168:171], v[192:195], v[102:105]
	v_mfma_f32_16x16x32_bf16 v[102:105], v[172:175], v[196:199], v[102:105]
	v_mfma_f32_16x16x32_bf16 v[86:89], v[168:171], v[206:209], v[86:89]
	v_mfma_f32_16x16x32_bf16 v[86:89], v[172:175], v[210:213], v[86:89]
	v_mfma_f32_16x16x32_bf16 v[70:73], v[168:171], v[214:217], v[70:73]
	v_mfma_f32_16x16x32_bf16 v[70:73], v[172:175], v[218:221], v[70:73]
	v_mfma_f32_16x16x32_bf16 v[114:117], v[176:179], v[184:187], v[114:117]
	v_mfma_f32_16x16x32_bf16 v[114:117], v[180:183], v[188:191], v[114:117]
	v_mfma_f32_16x16x32_bf16 v[98:101], v[176:179], v[192:195], v[98:101]
	v_mfma_f32_16x16x32_bf16 v[98:101], v[180:183], v[196:199], v[98:101]
	v_mfma_f32_16x16x32_bf16 v[82:85], v[176:179], v[206:209], v[82:85]
	v_mfma_f32_16x16x32_bf16 v[82:85], v[180:183], v[210:213], v[82:85]
	v_mfma_f32_16x16x32_bf16 v[66:69], v[176:179], v[214:217], v[66:69]
	v_mfma_f32_16x16x32_bf16 v[66:69], v[180:183], v[218:221], v[66:69]
	s_setprio 0
	s_barrier
	ds_read_b128 v[184:187], v154 offset:49152
	ds_read_b128 v[188:191], v154 offset:50176
	s_add_i32 m0, s1, 0x18000
	ds_read_b128 v[192:195], v154 offset:51200
	global_load_lds_dwordx4 v132, s[98:99]
	s_add_i32 m0, s1, 0x1a000
	ds_read_b128 v[196:199], v154 offset:52224
	global_load_lds_dwordx4 v136, s[98:99]
	s_add_i32 m0, s1, 0x1c000
	ds_read_b128 v[206:209], v154 offset:53248
	global_load_lds_dwordx4 v132, s[24:25]
	s_add_i32 m0, s1, 0x1e000
	ds_read_b128 v[210:213], v154 offset:54272
	global_load_lds_dwordx4 v136, s[24:25]
	s_add_i32 m0, s1, 0x8000
	ds_read_b128 v[214:217], v154 offset:55296
	global_load_lds_dwordx4 v130, s[44:45]
	s_add_i32 m0, s1, 0xa000
	ds_read_b128 v[218:221], v154 offset:56320
	global_load_lds_dwordx4 v134, s[44:45]
	s_waitcnt vmcnt(8) lgkmcnt(0)
	s_barrier
	s_setprio 1
	v_mfma_f32_16x16x32_bf16 v[62:65], v[146:149], v[184:187], v[62:65]
	v_mfma_f32_16x16x32_bf16 v[62:65], v[156:159], v[188:191], v[62:65]
	v_mfma_f32_16x16x32_bf16 v[46:49], v[146:149], v[192:195], v[46:49]
	v_mfma_f32_16x16x32_bf16 v[46:49], v[156:159], v[196:199], v[46:49]
	v_mfma_f32_16x16x32_bf16 v[30:33], v[146:149], v[206:209], v[30:33]
	v_mfma_f32_16x16x32_bf16 v[30:33], v[156:159], v[210:213], v[30:33]
	v_mfma_f32_16x16x32_bf16 v[14:17], v[146:149], v[214:217], v[14:17]
	v_mfma_f32_16x16x32_bf16 v[14:17], v[156:159], v[218:221], v[14:17]
	v_mfma_f32_16x16x32_bf16 v[58:61], v[160:163], v[184:187], v[58:61]
	v_mfma_f32_16x16x32_bf16 v[58:61], v[164:167], v[188:191], v[58:61]
	v_mfma_f32_16x16x32_bf16 v[42:45], v[160:163], v[192:195], v[42:45]
	v_mfma_f32_16x16x32_bf16 v[42:45], v[164:167], v[196:199], v[42:45]
	v_mfma_f32_16x16x32_bf16 v[26:29], v[160:163], v[206:209], v[26:29]
	v_mfma_f32_16x16x32_bf16 v[26:29], v[164:167], v[210:213], v[26:29]
	v_mfma_f32_16x16x32_bf16 v[10:13], v[160:163], v[214:217], v[10:13]
	v_mfma_f32_16x16x32_bf16 v[10:13], v[164:167], v[218:221], v[10:13]
	v_mfma_f32_16x16x32_bf16 v[54:57], v[168:171], v[184:187], v[54:57]
	v_mfma_f32_16x16x32_bf16 v[54:57], v[172:175], v[188:191], v[54:57]
	v_mfma_f32_16x16x32_bf16 v[38:41], v[168:171], v[192:195], v[38:41]
	v_mfma_f32_16x16x32_bf16 v[38:41], v[172:175], v[196:199], v[38:41]
	s_add_i32 s61, s61, 2
	v_mfma_f32_16x16x32_bf16 v[22:25], v[168:171], v[206:209], v[22:25]
	v_mfma_f32_16x16x32_bf16 v[22:25], v[172:175], v[210:213], v[22:25]
	s_add_u32 s59, s59, 0x100000
	v_mfma_f32_16x16x32_bf16 v[6:9], v[168:171], v[214:217], v[6:9]
	v_mfma_f32_16x16x32_bf16 v[6:9], v[172:175], v[218:221], v[6:9]
	s_addc_u32 s60, s60, 0
	v_mfma_f32_16x16x32_bf16 v[50:53], v[176:179], v[184:187], v[50:53]
	v_mfma_f32_16x16x32_bf16 v[50:53], v[180:183], v[188:191], v[50:53]
	s_add_u32 s42, s42, 0x400000
	v_mfma_f32_16x16x32_bf16 v[34:37], v[176:179], v[192:195], v[34:37]
	v_mfma_f32_16x16x32_bf16 v[34:37], v[180:183], v[196:199], v[34:37]
	s_addc_u32 s43, s43, 0
	v_mfma_f32_16x16x32_bf16 v[18:21], v[176:179], v[206:209], v[18:21]
	v_mfma_f32_16x16x32_bf16 v[18:21], v[180:183], v[210:213], v[18:21]
	s_cmpk_gt_u32 s61, 0xa9
	v_mfma_f32_16x16x32_bf16 v[2:5], v[176:179], v[214:217], v[2:5]
	v_mfma_f32_16x16x32_bf16 v[2:5], v[180:183], v[218:221], v[2:5]
	s_setprio 0
	s_barrier
	s_cbranch_scc0 .LBB0_834
	s_and_b64 vcc, exec, s[18:19]
	s_cbranch_vccz .LBB0_837
	s_barrier
